# best_v4 + SO4: hand-written first part of the scan S5 stage (G MFMAs, causal masks by 8 compares, A_bb/AKB/AOF stores)
# speedup vs baseline: 1.0294x; 1.0005x over previous
.LBB0_424:
	s_or_b64 exec, exec, s[10:11]
	v_lshlrev_b32_e32 v216, 5, v90
	v_lshlrev_b32_e32 v134, 2, v125
	s_andn2_b64 vcc, exec, s[82:83]
	v_lshlrev_b32_e32 v127, 4, v125
	v_add_u32_e32 v131, 64, v216
	v_add_u32_e32 v133, 0x80, v216
	v_add_u32_e32 v135, 0xc0, v216
	v_or_b32_e32 v132, 2, v134
	v_or_b32_e32 v130, 3, v134
	s_cbranch_vccnz .LBB0_436
	v_lshlrev_b32_e32 v51, 4, v125
	v_and_b32_e32 v92, 0x3e0, v216
	v_add_u32_e32 v50, v92, v51
	v_add_u32_e32 v92, s7, v50
	ds_read_b128 v[52:55], v92 offset:16384
	ds_read_b128 v[56:59], v92
	v_and_b32_e32 v93, 0x3e0, v131
	v_add3_u32 v93, v93, v51, s7
	ds_read_b128 v[60:63], v93 offset:17408
	ds_read_b128 v[64:67], v93 offset:1024
	v_and_b32_e32 v93, 0x3e0, v133
	v_add3_u32 v93, v93, v51, s7
	ds_read_b128 v[68:71], v93 offset:18432
	ds_read_b128 v[72:75], v93 offset:2048
	v_and_b32_e32 v93, 0x3e0, v135
	v_add3_u32 v93, v93, v51, s7
	ds_read_b128 v[76:79], v93 offset:19456
	ds_read_b128 v[80:83], v93 offset:3072
	v_and_b32_e32 v175, 15, v90
	v_lshrrev_b32_e32 v100, 4, v128
	s_waitcnt lgkmcnt(6)
	v_mfma_f32_32x32x16_f16 v[34:49], v[52:55], v[56:59], 0
	v_add_u32_e32 v100, v175, v100
	s_waitcnt lgkmcnt(4)
	v_mfma_f32_32x32x16_f16 v[34:49], v[60:63], v[64:67], v[34:49]
	v_sub_u32_e32 v100, v100, v134
	s_waitcnt lgkmcnt(2)
	v_mfma_f32_32x32x16_f16 v[34:49], v[68:71], v[72:75], v[34:49]
	s_waitcnt lgkmcnt(0)
	v_mfma_f32_32x32x16_f16 v[34:49], v[76:79], v[80:83], v[34:49]
	v_cmp_lt_i32_e64 s[14:15], 0, v100
	v_cmp_lt_i32_e64 s[16:17], 1, v100
	v_cmp_lt_i32_e64 s[18:19], 2, v100
	v_cmp_lt_i32_e64 s[20:21], 3, v100
	v_cmp_lt_i32_e64 s[22:23], 8, v100
	v_cmp_lt_i32_e64 s[24:25], 9, v100
	v_cmp_lt_i32_e64 s[26:27], 10, v100
	v_cmp_lt_i32_e64 s[28:29], 11, v100
	v_lshlrev_b32_e32 v92, 8, v125
	v_lshlrev_b32_e32 v93, 2, v175
	v_add3_u32 v92, s44, v92, v93
	v_add_u32_e32 v93, s51, v50
	v_add_u32_e32 v101, s5, v50
	v_cndmask_b32_e64 v34, 0, v34, s[14:15]
	v_cndmask_b32_e64 v35, 0, v35, s[16:17]
	v_cndmask_b32_e64 v36, 0, v36, s[18:19]
	v_cndmask_b32_e64 v37, 0, v37, s[20:21]
	v_cndmask_b32_e64 v38, 0, v38, s[22:23]
	v_cndmask_b32_e64 v39, 0, v39, s[24:25]
	v_cndmask_b32_e64 v40, 0, v40, s[26:27]
	v_cndmask_b32_e64 v41, 0, v41, s[28:29]
	v_cndmask_b32_e64 v42, 0, v42, s[14:15]
	v_cndmask_b32_e64 v43, 0, v43, s[16:17]
	v_cndmask_b32_e64 v44, 0, v44, s[18:19]
	v_cndmask_b32_e64 v45, 0, v45, s[20:21]
	v_cndmask_b32_e64 v46, 0, v46, s[22:23]
	v_cndmask_b32_e64 v47, 0, v47, s[24:25]
	v_cndmask_b32_e64 v48, 0, v48, s[26:27]
	v_cndmask_b32_e64 v49, 0, v49, s[28:29]
	v_cmp_gt_u32_e32 vcc, 16, v128
	v_cvt_pk_f16_f32 v84, v34, v35
	v_cvt_pk_f16_f32 v85, v36, v37
	v_cvt_pk_f16_f32 v86, v38, v39
	v_cvt_pk_f16_f32 v87, v40, v41
	v_cvt_pk_f16_f32 v96, v42, v43
	v_cvt_pk_f16_f32 v97, v44, v45
	v_cvt_pk_f16_f32 v98, v46, v47
	v_cvt_pk_f16_f32 v99, v48, v49
	v_cndmask_b32_e32 v52, 0, v96, vcc
	v_cndmask_b32_e32 v53, 0, v97, vcc
	v_cndmask_b32_e32 v54, 0, v98, vcc
	v_cndmask_b32_e32 v55, 0, v99, vcc
	v_cndmask_b32_e64 v56, v84, 0, vcc
	v_cndmask_b32_e64 v57, v85, 0, vcc
	v_cndmask_b32_e64 v58, v86, 0, vcc
	v_cndmask_b32_e64 v59, v87, 0, vcc
	v_cndmask_b32_e64 v60, v96, 0, vcc
	v_cndmask_b32_e64 v61, v97, 0, vcc
	v_cndmask_b32_e64 v62, v98, 0, vcc
	v_cndmask_b32_e64 v63, v99, 0, vcc
	ds_write_b128 v93, v[52:55]
	ds_write_b128 v101, v[56:59]
	ds_write_b128 v101, v[60:63] offset:1024
	s_and_saveexec_b64 s[10:11], vcc
	ds_write2_b32 v92, v34, v35 offset1:16
	ds_write2_b32 v92, v36, v37 offset0:32 offset1:48
	ds_write2_b32 v92, v38, v39 offset0:128 offset1:144
	ds_write2_b32 v92, v40, v41 offset0:160 offset1:176
	s_or_b64 exec, exec, s[10:11]
	s_waitcnt lgkmcnt(0)
	v_cmp_lt_i32_e32 vcc, 15, v90
	s_and_saveexec_b64 s[10:11], vcc
	s_xor_b64 s[10:11], exec, s[10:11]
	s_cbranch_execz .LBB0_433
	v_cmp_gt_u32_e32 vcc, 32, v90
	s_and_saveexec_b64 s[14:15], vcc
	s_cbranch_execz .LBB0_432
	s_mov_b32 s40, s41
	s_waitcnt lgkmcnt(11)
	v_add_u32_e32 v34, s42, v216
	s_mov_b32 s16, s42
	s_mov_b32 s42, s41
	s_mov_b32 s43, s41
	s_waitcnt lgkmcnt(8)
	v_mov_b64_e32 v[36:37], s[40:41]
	v_mov_b64_e32 v[38:39], s[42:43]
	s_mov_b32 s42, s16
	ds_write_b128 v34, v[36:39]
	ds_write_b128 v34, v[36:39] offset:16
